# stack on the max-reuse MFMA order: pool sliding-window specialization, unaligned P1 epilogues, short P3 RS test
# speedup vs baseline: 1.0007x; 1.0007x over previous
; #define PG8_STAGE(bufoff, gbase, voff) do { _Pragma("unroll") for (int _i = 0; _i < 2; ++_i) \
;         __builtin_amdgcn_global_load_lds((const unsigned*)((const char*)(gbase) + (voff)[_i]), (PG8_LAS unsigned*)(lds + (bufoff) + ldsw + _i * 8192), 16, 0, 0); } while (0)
; #define PG8_LDA(dst, b, h) do { _Pragma("unroll") for (int m = 0; m < 4; ++m) _Pragma("unroll") for (int k = 0; k < 2; ++k) dst[m][k] = *(const PG8_LAS bf16x8*)(lds + PG8_SA(b, h) + aoff + m * 2048 + k * 1024); } while (0)
; #define PG8_LDB(dst, b, h) do { _Pragma("unroll") for (int n = 0; n < 2; ++n) _Pragma("unroll") for (int k = 0; k < 2; ++k) dst[n][k] = *(const PG8_LAS bf16x8*)(lds + PG8_SB(b, h) + boff + n * 2048 + k * 1024); } while (0)
; #define PG8_MMA(ai, bj, At, Bt) do { __builtin_amdgcn_s_setprio(1); _Pragma("unroll") for (int m = 0; m < 4; ++m) _Pragma("unroll") for (int n = 0; n < 2; ++n) _Pragma("unroll") for (int k = 0; k < 2; ++k) \
;         acc[ai][bj][m][n] = __builtin_amdgcn_mfma_f32_16x16x32_bf16(Bt[n][k], At[m][k], acc[ai][bj][m][n], 0, 0, 0); __builtin_amdgcn_s_setprio(0); } while (0)
; #define PG8_WAIT_V(n) asm volatile("s_waitcnt vmcnt(" #n ")" ::: "memory")
; #define PG8_BAR __builtin_amdgcn_s_barrier()
; template <class Epi, class Sched, bool ALIGN_EPI = false, bool SP2 = false, bool RS = false, bool BPRE = false>
; __device__ __forceinline__ void gemm_phase(PG8_LAS unsigned char* lds, const Gemm g, const Sched& S, const Epi& E, const float* rs_ss = nullptr, PG8_LAS float* rs_tab = nullptr) {
;     ...
;             const char* a1 = cA + (size_t)(t + 1) * kstep;
;             const char* a2 = last ? nA : cA + (size_t)(t + 2) * kstep; const char* b2 = last ? nB : cB + (size_t)(t + 2) * kstep;
;             const char* a3 = a2 + kstep; const char* b3 = b2 + kstep;
;             if (last && has_next) S.a_ready(nxt);
;             if constexpr (SP2) {
;             PG8_LDB(B0, 0, 0); PG8_LDB(B1, 0, 1); PG8_SCHED; PG8_LDA(At, 0, 0); PG8_STAGE(PG8_SA(1, 1), a1 + hstep, voffA);
;             PG8_WAIT_V(8); PG8_WAIT_L(0); PG8_BAR; PG8_MMA(0, 0, At, B0); PG8_MMA(0, 1, At, B1); PG8_BAR; PG8_SCHED;
;             PG8_LDA(At, 0, 1); PG8_STAGE(PG8_SB(0, 0), b2, voffB); PG8_STAGE(PG8_SB(0, 1), b2 + hstep, voffB); PG8_STAGE(PG8_SA(0, 0), a2, voffA);
;             PG8_WAIT_V(8); PG8_WAIT_L(0); PG8_BAR; PG8_MMA(1, 0, At, B0); PG8_MMA(1, 1, At, B1); PG8_BAR; PG8_SCHED;
.LBB0_196:
	ds_read_b128 v[130:133], v161
	ds_read_b128 v[134:137], v161 offset:1024
	ds_read_b128 v[152:155], v161 offset:2048
	ds_read_b128 v[156:159], v161 offset:3072
	ds_read_b128 v[166:169], v162
	ds_read_b128 v[170:173], v162 offset:1024
	ds_read_b128 v[174:177], v162 offset:2048
	ds_read_b128 v[182:185], v162 offset:3072
	s_add_u32 s58, s56, 0xfff84000
	s_addc_u32 s59, s57, -1
	s_cmp_eq_u32 s89, 28
	s_cselect_b32 s70, s19, s58
	s_cselect_b32 s71, s5, s59
	s_cselect_b32 s60, s47, s87
	s_cselect_b32 s61, s17, s88
	s_add_u32 s58, s70, 0x4000
	s_addc_u32 s59, s71, 0
	v_lshl_add_u64 v[178:179], s[56:57], 0, v[138:139]
	s_add_i32 m0, s72, 0xc000
	ds_read_b128 v[188:191], v163
	ds_read_b128 v[192:195], v163 offset:1024
	ds_read_b128 v[196:199], v163 offset:2048
	ds_read_b128 v[200:203], v163 offset:3072
	ds_read_b128 v[204:207], v163 offset:4096
	ds_read_b128 v[208:211], v163 offset:5120
	ds_read_b128 v[212:215], v163 offset:6144
	ds_read_b128 v[216:219], v163 offset:7168
	global_load_lds_dwordx4 v[178:179], off
	v_lshl_add_u64 v[178:179], s[56:57], 0, v[146:147]
	s_add_i32 m0, s72, 0xe000
	s_nop 0
	global_load_lds_dwordx4 v[178:179], off
	s_waitcnt vmcnt(8)
	s_waitcnt lgkmcnt(0)
	s_barrier
	s_setprio 1
	s_waitcnt lgkmcnt(0)
	v_mfma_f32_16x16x32_bf16 v[126:129], v[130:133], v[188:191], v[126:129]
	v_mfma_f32_16x16x32_bf16 v[126:129], v[134:137], v[192:195], v[126:129]
	v_mfma_f32_16x16x32_bf16 v[122:125], v[156:159], v[192:195], v[122:125]
	v_mfma_f32_16x16x32_bf16 v[122:125], v[152:155], v[188:191], v[122:125]
	v_mfma_f32_16x16x32_bf16 v[106:109], v[152:155], v[196:199], v[106:109]
	v_mfma_f32_16x16x32_bf16 v[106:109], v[156:159], v[200:203], v[106:109]
	v_mfma_f32_16x16x32_bf16 v[110:113], v[134:137], v[200:203], v[110:113]
	v_mfma_f32_16x16x32_bf16 v[110:113], v[130:133], v[196:199], v[110:113]
	v_mfma_f32_16x16x32_bf16 v[94:97], v[130:133], v[204:207], v[94:97]
	v_mfma_f32_16x16x32_bf16 v[94:97], v[134:137], v[208:211], v[94:97]
	v_mfma_f32_16x16x32_bf16 v[90:93], v[156:159], v[208:211], v[90:93]
	v_mfma_f32_16x16x32_bf16 v[90:93], v[152:155], v[204:207], v[90:93]
	v_mfma_f32_16x16x32_bf16 v[74:77], v[152:155], v[212:215], v[74:77]
	v_mfma_f32_16x16x32_bf16 v[74:77], v[156:159], v[216:219], v[74:77]
	v_mfma_f32_16x16x32_bf16 v[78:81], v[134:137], v[216:219], v[78:81]
	v_mfma_f32_16x16x32_bf16 v[78:81], v[130:133], v[212:215], v[78:81]
	s_setprio 0
	s_setprio 1
	v_mfma_f32_16x16x32_bf16 v[70:73], v[166:169], v[212:215], v[70:73]
	v_mfma_f32_16x16x32_bf16 v[70:73], v[170:173], v[216:219], v[70:73]
	v_mfma_f32_16x16x32_bf16 v[66:69], v[182:185], v[216:219], v[66:69]
	v_mfma_f32_16x16x32_bf16 v[66:69], v[174:177], v[212:215], v[66:69]
	v_mfma_f32_16x16x32_bf16 v[82:85], v[174:177], v[204:207], v[82:85]
	v_mfma_f32_16x16x32_bf16 v[82:85], v[182:185], v[208:211], v[82:85]
	v_mfma_f32_16x16x32_bf16 v[86:89], v[170:173], v[208:211], v[86:89]
	v_mfma_f32_16x16x32_bf16 v[86:89], v[166:169], v[204:207], v[86:89]
	v_mfma_f32_16x16x32_bf16 v[102:105], v[166:169], v[196:199], v[102:105]
	v_mfma_f32_16x16x32_bf16 v[102:105], v[170:173], v[200:203], v[102:105]
	v_mfma_f32_16x16x32_bf16 v[98:101], v[182:185], v[200:203], v[98:101]
	v_mfma_f32_16x16x32_bf16 v[98:101], v[174:177], v[196:199], v[98:101]
	v_mfma_f32_16x16x32_bf16 v[114:117], v[174:177], v[188:191], v[114:117]
	v_mfma_f32_16x16x32_bf16 v[114:117], v[182:185], v[192:195], v[114:117]
	v_mfma_f32_16x16x32_bf16 v[118:121], v[170:173], v[192:195], v[118:121]
	v_mfma_f32_16x16x32_bf16 v[118:121], v[166:169], v[188:191], v[118:121]
	s_setprio 0
	s_barrier
	s_add_i32 s90, s83, s15
	v_lshl_add_u64 v[178:179], s[60:61], 0, v[138:139]
	s_mov_b32 m0, s90
	ds_read_b128 v[188:191], v163 offset:16384
	ds_read_b128 v[192:195], v163 offset:17408
	ds_read_b128 v[196:199], v163 offset:18432
	ds_read_b128 v[200:203], v163 offset:19456
	ds_read_b128 v[204:207], v163 offset:20480
	ds_read_b128 v[208:211], v163 offset:21504
	ds_read_b128 v[212:215], v163 offset:22528
	ds_read_b128 v[216:219], v163 offset:23552
	global_load_lds_dwordx4 v[178:179], off
	s_add_i32 m0, s90, 0x2000
	s_add_u32 s90, s60, 0x80000
	v_lshl_add_u64 v[178:179], s[60:61], 0, v[140:141]
	s_addc_u32 s91, s61, 0
	s_add_i32 s92, s86, s15
	global_load_lds_dwordx4 v[178:179], off
	v_lshl_add_u64 v[178:179], s[90:91], 0, v[138:139]
	s_mov_b32 m0, s92
	s_nop 0
	global_load_lds_dwordx4 v[178:179], off
	v_lshl_add_u64 v[178:179], s[90:91], 0, v[140:141]
	s_add_i32 m0, s92, 0x2000
	s_nop 0
	global_load_lds_dwordx4 v[178:179], off
	v_lshl_add_u64 v[178:179], s[70:71], 0, v[138:139]
	s_mov_b32 m0, s72
	s_nop 0
	global_load_lds_dwordx4 v[178:179], off
	v_lshl_add_u64 v[178:179], s[70:71], 0, v[140:141]
	s_mov_b32 m0, s73
	s_nop 0
	global_load_lds_dwordx4 v[178:179], off
	s_waitcnt vmcnt(8)
	s_waitcnt lgkmcnt(0)
	s_barrier
; #define PG8_STAGE(bufoff, gbase, voff) do { _Pragma("unroll") for (int _i = 0; _i < 2; ++_i) \
;         __builtin_amdgcn_global_load_lds((const unsigned*)((const char*)(gbase) + (voff)[_i]), (PG8_LAS unsigned*)(lds + (bufoff) + ldsw + _i * 8192), 16, 0, 0); } while (0)
; #define PG8_LDA(dst, b, h) do { _Pragma("unroll") for (int m = 0; m < 4; ++m) _Pragma("unroll") for (int k = 0; k < 2; ++k) dst[m][k] = *(const PG8_LAS bf16x8*)(lds + PG8_SA(b, h) + aoff + m * 2048 + k * 1024); } while (0)
; #define PG8_LDB(dst, b, h) do { _Pragma("unroll") for (int n = 0; n < 2; ++n) _Pragma("unroll") for (int k = 0; k < 2; ++k) dst[n][k] = *(const PG8_LAS bf16x8*)(lds + PG8_SB(b, h) + boff + n * 2048 + k * 1024); } while (0)
; #define PG8_MMA(ai, bj, At, Bt) do { __builtin_amdgcn_s_setprio(1); _Pragma("unroll") for (int m = 0; m < 4; ++m) _Pragma("unroll") for (int n = 0; n < 2; ++n) _Pragma("unroll") for (int k = 0; k < 2; ++k) \
;         acc[ai][bj][m][n] = __builtin_amdgcn_mfma_f32_16x16x32_bf16(Bt[n][k], At[m][k], acc[ai][bj][m][n], 0, 0, 0); __builtin_amdgcn_s_setprio(0); } while (0)
; #define PG8_WAIT_V(n) asm volatile("s_waitcnt vmcnt(" #n ")" ::: "memory")
; #define PG8_WAIT_L(n) asm volatile("s_waitcnt lgkmcnt(" #n ")" ::: "memory")
; #define PG8_BAR __builtin_amdgcn_s_barrier()
; #define PG8_SCHED __builtin_amdgcn_sched_barrier(0)
; template <class Epi, class Sched, bool ALIGN_EPI = false, bool SP2 = false, bool RS = false, bool BPRE = false>
; __device__ __forceinline__ void gemm_phase(PG8_LAS unsigned char* lds, const Gemm g, const Sched& S, const Epi& E, const float* rs_ss = nullptr, PG8_LAS float* rs_tab = nullptr) {
;     ...
;             PG8_WAIT_V(8); PG8_WAIT_L(0); PG8_BAR; PG8_MMA(1, 0, At, B0); PG8_MMA(1, 1, At, B1); PG8_BAR; PG8_SCHED;
;             PG8_LDB(B0, 1, 0); PG8_LDB(B1, 1, 1); PG8_SCHED; PG8_LDA(At, 1, 0); PG8_STAGE(PG8_SA(0, 1), a2 + hstep, voffA);
;             PG8_WAIT_V(8); PG8_WAIT_L(0); PG8_BAR; PG8_MMA(0, 0, At, B0); PG8_MMA(0, 1, At, B1); PG8_BAR; PG8_SCHED;
;             PG8_LDA(At, 1, 1); PG8_STAGE(PG8_SB(1, 0), b3, voffB); PG8_STAGE(PG8_SB(1, 1), b3 + hstep, voffB); PG8_STAGE(PG8_SA(1, 0), a3, voffA);
;             PG8_WAIT_V(8); PG8_WAIT_L(0); PG8_BAR; PG8_MMA(1, 0, At, B0); PG8_MMA(1, 1, At, B1); PG8_BAR; PG8_SCHED;
	s_setprio 1
	s_waitcnt lgkmcnt(0)
	v_mfma_f32_16x16x32_bf16 v[62:65], v[130:133], v[188:191], v[62:65]
	v_mfma_f32_16x16x32_bf16 v[62:65], v[134:137], v[192:195], v[62:65]
	v_mfma_f32_16x16x32_bf16 v[58:61], v[156:159], v[192:195], v[58:61]
	v_mfma_f32_16x16x32_bf16 v[58:61], v[152:155], v[188:191], v[58:61]
	v_mfma_f32_16x16x32_bf16 v[42:45], v[152:155], v[196:199], v[42:45]
	v_mfma_f32_16x16x32_bf16 v[42:45], v[156:159], v[200:203], v[42:45]
	v_mfma_f32_16x16x32_bf16 v[46:49], v[134:137], v[200:203], v[46:49]
	v_mfma_f32_16x16x32_bf16 v[46:49], v[130:133], v[196:199], v[46:49]
	v_mfma_f32_16x16x32_bf16 v[30:33], v[130:133], v[204:207], v[30:33]
	v_mfma_f32_16x16x32_bf16 v[30:33], v[134:137], v[208:211], v[30:33]
	v_mfma_f32_16x16x32_bf16 v[26:29], v[156:159], v[208:211], v[26:29]
	v_mfma_f32_16x16x32_bf16 v[26:29], v[152:155], v[204:207], v[26:29]
	v_mfma_f32_16x16x32_bf16 v[10:13], v[152:155], v[212:215], v[10:13]
	v_mfma_f32_16x16x32_bf16 v[10:13], v[156:159], v[216:219], v[10:13]
	v_mfma_f32_16x16x32_bf16 v[14:17], v[134:137], v[216:219], v[14:17]
	v_mfma_f32_16x16x32_bf16 v[14:17], v[130:133], v[212:215], v[14:17]
	s_setprio 0
	s_setprio 1
	v_mfma_f32_16x16x32_bf16 v[6:9], v[166:169], v[212:215], v[6:9]
	v_mfma_f32_16x16x32_bf16 v[6:9], v[170:173], v[216:219], v[6:9]
	v_mfma_f32_16x16x32_bf16 v[2:5], v[182:185], v[216:219], v[2:5]
	v_mfma_f32_16x16x32_bf16 v[2:5], v[174:177], v[212:215], v[2:5]
	v_mfma_f32_16x16x32_bf16 v[18:21], v[174:177], v[204:207], v[18:21]
	v_mfma_f32_16x16x32_bf16 v[18:21], v[182:185], v[208:211], v[18:21]
	v_mfma_f32_16x16x32_bf16 v[22:25], v[170:173], v[208:211], v[22:25]
	v_mfma_f32_16x16x32_bf16 v[22:25], v[166:169], v[204:207], v[22:25]
	v_mfma_f32_16x16x32_bf16 v[38:41], v[166:169], v[196:199], v[38:41]
	v_mfma_f32_16x16x32_bf16 v[38:41], v[170:173], v[200:203], v[38:41]
	v_mfma_f32_16x16x32_bf16 v[34:37], v[182:185], v[200:203], v[34:37]
	v_mfma_f32_16x16x32_bf16 v[34:37], v[174:177], v[196:199], v[34:37]
	v_mfma_f32_16x16x32_bf16 v[50:53], v[174:177], v[188:191], v[50:53]
	v_mfma_f32_16x16x32_bf16 v[50:53], v[182:185], v[192:195], v[50:53]
	v_mfma_f32_16x16x32_bf16 v[54:57], v[170:173], v[192:195], v[54:57]
	v_mfma_f32_16x16x32_bf16 v[54:57], v[166:169], v[188:191], v[54:57]
	s_setprio 0
	s_barrier
	s_add_i32 s90, 0, 0x18000
	v_add_u32_e32 v143, s90, v160
	s_add_i32 s91, 0, 0x1c000
	ds_read_b128 v[130:133], v143
	ds_read_b128 v[134:137], v143 offset:1024
	ds_read_b128 v[152:155], v143 offset:2048
	ds_read_b128 v[156:159], v143 offset:3072
	v_add_u32_e32 v143, s91, v160
	ds_read_b128 v[166:169], v143
	ds_read_b128 v[170:173], v143 offset:1024
	ds_read_b128 v[174:177], v143 offset:2048
	ds_read_b128 v[182:185], v143 offset:3072
	s_add_u32 s70, s70, 0x80000
	s_addc_u32 s71, s71, 0
	s_mov_b32 m0, s74
	v_lshl_add_u64 v[178:179], s[70:71], 0, v[138:139]
	ds_read_b128 v[188:191], v163 offset:32768
	ds_read_b128 v[192:195], v163 offset:33792
	ds_read_b128 v[196:199], v163 offset:34816
	ds_read_b128 v[200:203], v163 offset:35840
	ds_read_b128 v[204:207], v163 offset:36864
	ds_read_b128 v[208:211], v163 offset:37888
	ds_read_b128 v[212:215], v163 offset:38912
	ds_read_b128 v[216:219], v163 offset:39936
	global_load_lds_dwordx4 v[178:179], off
	v_lshl_add_u64 v[178:179], s[70:71], 0, v[140:141]
	s_mov_b32 m0, s75
	s_nop 0
	global_load_lds_dwordx4 v[178:179], off
	s_waitcnt vmcnt(8)
	s_waitcnt lgkmcnt(0)
	s_barrier
	s_setprio 1
	s_waitcnt lgkmcnt(0)
	v_mfma_f32_16x16x32_bf16 v[126:129], v[130:133], v[188:191], v[126:129]
	v_mfma_f32_16x16x32_bf16 v[126:129], v[134:137], v[192:195], v[126:129]
	v_mfma_f32_16x16x32_bf16 v[122:125], v[156:159], v[192:195], v[122:125]
	v_mfma_f32_16x16x32_bf16 v[122:125], v[152:155], v[188:191], v[122:125]
	v_mfma_f32_16x16x32_bf16 v[106:109], v[152:155], v[196:199], v[106:109]
	v_mfma_f32_16x16x32_bf16 v[106:109], v[156:159], v[200:203], v[106:109]
	v_mfma_f32_16x16x32_bf16 v[110:113], v[134:137], v[200:203], v[110:113]
	v_mfma_f32_16x16x32_bf16 v[110:113], v[130:133], v[196:199], v[110:113]
	v_mfma_f32_16x16x32_bf16 v[94:97], v[130:133], v[204:207], v[94:97]
	v_mfma_f32_16x16x32_bf16 v[94:97], v[134:137], v[208:211], v[94:97]
	v_mfma_f32_16x16x32_bf16 v[90:93], v[156:159], v[208:211], v[90:93]
	v_mfma_f32_16x16x32_bf16 v[90:93], v[152:155], v[204:207], v[90:93]
	v_mfma_f32_16x16x32_bf16 v[74:77], v[152:155], v[212:215], v[74:77]
	v_mfma_f32_16x16x32_bf16 v[74:77], v[156:159], v[216:219], v[74:77]
	v_mfma_f32_16x16x32_bf16 v[78:81], v[134:137], v[216:219], v[78:81]
	v_mfma_f32_16x16x32_bf16 v[78:81], v[130:133], v[212:215], v[78:81]
	s_setprio 0
	s_setprio 1
	v_mfma_f32_16x16x32_bf16 v[70:73], v[166:169], v[212:215], v[70:73]
	v_mfma_f32_16x16x32_bf16 v[70:73], v[170:173], v[216:219], v[70:73]
	v_mfma_f32_16x16x32_bf16 v[66:69], v[182:185], v[216:219], v[66:69]
	v_mfma_f32_16x16x32_bf16 v[66:69], v[174:177], v[212:215], v[66:69]
	v_mfma_f32_16x16x32_bf16 v[82:85], v[174:177], v[204:207], v[82:85]
	v_mfma_f32_16x16x32_bf16 v[82:85], v[182:185], v[208:211], v[82:85]
	v_mfma_f32_16x16x32_bf16 v[86:89], v[170:173], v[208:211], v[86:89]
	v_mfma_f32_16x16x32_bf16 v[86:89], v[166:169], v[204:207], v[86:89]
	v_mfma_f32_16x16x32_bf16 v[102:105], v[166:169], v[196:199], v[102:105]
	v_mfma_f32_16x16x32_bf16 v[102:105], v[170:173], v[200:203], v[102:105]
	v_mfma_f32_16x16x32_bf16 v[98:101], v[182:185], v[200:203], v[98:101]
	v_mfma_f32_16x16x32_bf16 v[98:101], v[174:177], v[196:199], v[98:101]
	v_mfma_f32_16x16x32_bf16 v[114:117], v[174:177], v[188:191], v[114:117]
	v_mfma_f32_16x16x32_bf16 v[114:117], v[182:185], v[192:195], v[114:117]
	v_mfma_f32_16x16x32_bf16 v[118:121], v[170:173], v[192:195], v[118:121]
	v_mfma_f32_16x16x32_bf16 v[118:121], v[166:169], v[188:191], v[118:121]
	s_setprio 0
	s_barrier
; #define PG8_STAGE(bufoff, gbase, voff) do { _Pragma("unroll") for (int _i = 0; _i < 2; ++_i) \
;         __builtin_amdgcn_global_load_lds((const unsigned*)((const char*)(gbase) + (voff)[_i]), (PG8_LAS unsigned*)(lds + (bufoff) + ldsw + _i * 8192), 16, 0, 0); } while (0)
; #define PG8_LDA(dst, b, h) do { _Pragma("unroll") for (int m = 0; m < 4; ++m) _Pragma("unroll") for (int k = 0; k < 2; ++k) dst[m][k] = *(const PG8_LAS bf16x8*)(lds + PG8_SA(b, h) + aoff + m * 2048 + k * 1024); } while (0)
; #define PG8_MMA(ai, bj, At, Bt) do { __builtin_amdgcn_s_setprio(1); _Pragma("unroll") for (int m = 0; m < 4; ++m) _Pragma("unroll") for (int n = 0; n < 2; ++n) _Pragma("unroll") for (int k = 0; k < 2; ++k) \
;         acc[ai][bj][m][n] = __builtin_amdgcn_mfma_f32_16x16x32_bf16(Bt[n][k], At[m][k], acc[ai][bj][m][n], 0, 0, 0); __builtin_amdgcn_s_setprio(0); } while (0)
; #define PG8_WAIT_V(n) asm volatile("s_waitcnt vmcnt(" #n ")" ::: "memory")
; #define PG8_WAIT_L(n) asm volatile("s_waitcnt lgkmcnt(" #n ")" ::: "memory")
; #define PG8_BAR __builtin_amdgcn_s_barrier()
; #define PG8_SCHED __builtin_amdgcn_sched_barrier(0)
; template <class Epi, class Sched, bool ALIGN_EPI = false, bool SP2 = false, bool RS = false, bool BPRE = false>
; __device__ __forceinline__ void gemm_phase(PG8_LAS unsigned char* lds, const Gemm g, const Sched& S, const Epi& E, const float* rs_ss = nullptr, PG8_LAS float* rs_tab = nullptr) {
;     ...
;         for (int t = 0; t < nt; t += 2) {
;     ...
;             PG8_LDA(At, 1, 1); PG8_STAGE(PG8_SB(1, 0), b3, voffB); PG8_STAGE(PG8_SB(1, 1), b3 + hstep, voffB); PG8_STAGE(PG8_SA(1, 0), a3, voffA);
;             PG8_WAIT_V(8); PG8_WAIT_L(0); PG8_BAR; PG8_MMA(1, 0, At, B0); PG8_MMA(1, 1, At, B1); PG8_BAR; PG8_SCHED;
;     ...
;         if constexpr (ALIGN_EPI) { if (wr == 0) PG8_BAR; }
	s_add_u32 s70, s60, 0x4000
	s_addc_u32 s71, s61, 0
	s_add_i32 s90, s90, s15
	v_lshl_add_u64 v[178:179], s[70:71], 0, v[138:139]
	s_mov_b32 m0, s90
	ds_read_b128 v[188:191], v163 offset:49152
	ds_read_b128 v[192:195], v163 offset:50176
	ds_read_b128 v[196:199], v163 offset:51200
	ds_read_b128 v[200:203], v163 offset:52224
	ds_read_b128 v[204:207], v163 offset:53248
	ds_read_b128 v[208:211], v163 offset:54272
	ds_read_b128 v[212:215], v163 offset:55296
	ds_read_b128 v[216:219], v163 offset:56320
	global_load_lds_dwordx4 v[178:179], off
	s_add_i32 m0, s90, 0x2000
	s_add_u32 s60, s60, 0x84000
	v_lshl_add_u64 v[178:179], s[70:71], 0, v[140:141]
	s_addc_u32 s61, s61, 0
	s_add_i32 s70, s91, s15
	global_load_lds_dwordx4 v[178:179], off
	v_lshl_add_u64 v[178:179], s[60:61], 0, v[138:139]
	s_mov_b32 m0, s70
	s_nop 0
	global_load_lds_dwordx4 v[178:179], off
	v_lshl_add_u64 v[178:179], s[60:61], 0, v[140:141]
	s_add_i32 m0, s70, 0x2000
	s_nop 0
	global_load_lds_dwordx4 v[178:179], off
	v_lshl_add_u64 v[178:179], s[58:59], 0, v[138:139]
	s_mov_b32 m0, s79
	s_nop 0
	global_load_lds_dwordx4 v[178:179], off
	v_lshl_add_u64 v[178:179], s[58:59], 0, v[140:141]
	s_mov_b32 m0, s80
	s_nop 0
	global_load_lds_dwordx4 v[178:179], off
	s_waitcnt vmcnt(8)
	s_waitcnt lgkmcnt(0)
	s_barrier
	s_setprio 1
	s_waitcnt lgkmcnt(0)
	v_mfma_f32_16x16x32_bf16 v[62:65], v[130:133], v[188:191], v[62:65]
	v_mfma_f32_16x16x32_bf16 v[62:65], v[134:137], v[192:195], v[62:65]
	v_mfma_f32_16x16x32_bf16 v[58:61], v[156:159], v[192:195], v[58:61]
	v_mfma_f32_16x16x32_bf16 v[58:61], v[152:155], v[188:191], v[58:61]
	v_mfma_f32_16x16x32_bf16 v[42:45], v[152:155], v[196:199], v[42:45]
	v_mfma_f32_16x16x32_bf16 v[42:45], v[156:159], v[200:203], v[42:45]
	v_mfma_f32_16x16x32_bf16 v[46:49], v[134:137], v[200:203], v[46:49]
	v_mfma_f32_16x16x32_bf16 v[46:49], v[130:133], v[196:199], v[46:49]
	v_mfma_f32_16x16x32_bf16 v[30:33], v[130:133], v[204:207], v[30:33]
	v_mfma_f32_16x16x32_bf16 v[30:33], v[134:137], v[208:211], v[30:33]
	v_mfma_f32_16x16x32_bf16 v[26:29], v[156:159], v[208:211], v[26:29]
	v_mfma_f32_16x16x32_bf16 v[26:29], v[152:155], v[204:207], v[26:29]
	v_mfma_f32_16x16x32_bf16 v[10:13], v[152:155], v[212:215], v[10:13]
	v_mfma_f32_16x16x32_bf16 v[10:13], v[156:159], v[216:219], v[10:13]
	v_mfma_f32_16x16x32_bf16 v[14:17], v[134:137], v[216:219], v[14:17]
	v_mfma_f32_16x16x32_bf16 v[14:17], v[130:133], v[212:215], v[14:17]
	s_setprio 0
	s_setprio 1
	v_mfma_f32_16x16x32_bf16 v[6:9], v[166:169], v[212:215], v[6:9]
	v_mfma_f32_16x16x32_bf16 v[6:9], v[170:173], v[216:219], v[6:9]
	v_mfma_f32_16x16x32_bf16 v[2:5], v[182:185], v[216:219], v[2:5]
	v_mfma_f32_16x16x32_bf16 v[2:5], v[174:177], v[212:215], v[2:5]
	v_mfma_f32_16x16x32_bf16 v[18:21], v[174:177], v[204:207], v[18:21]
	v_mfma_f32_16x16x32_bf16 v[18:21], v[182:185], v[208:211], v[18:21]
	v_mfma_f32_16x16x32_bf16 v[22:25], v[170:173], v[208:211], v[22:25]
	v_mfma_f32_16x16x32_bf16 v[22:25], v[166:169], v[204:207], v[22:25]
	v_mfma_f32_16x16x32_bf16 v[38:41], v[166:169], v[196:199], v[38:41]
	v_mfma_f32_16x16x32_bf16 v[38:41], v[170:173], v[200:203], v[38:41]
	v_mfma_f32_16x16x32_bf16 v[34:37], v[182:185], v[200:203], v[34:37]
	v_mfma_f32_16x16x32_bf16 v[34:37], v[174:177], v[196:199], v[34:37]
	v_mfma_f32_16x16x32_bf16 v[50:53], v[174:177], v[188:191], v[50:53]
	v_mfma_f32_16x16x32_bf16 v[50:53], v[182:185], v[192:195], v[50:53]
	v_mfma_f32_16x16x32_bf16 v[54:57], v[170:173], v[192:195], v[54:57]
	v_mfma_f32_16x16x32_bf16 v[54:57], v[166:169], v[188:191], v[54:57]
	s_setprio 0
	s_barrier
	s_add_i32 s89, s89, 2
	s_add_u32 s56, s56, 0x8000
	s_addc_u32 s57, s57, 0
	s_add_u32 s87, s87, 0x8000
	s_addc_u32 s88, s88, 0
	s_cmp_gt_u32 s89, 29
	s_cbranch_scc0 .LBB0_196
	s_andn2_b64 vcc, s[12:13], s[6:7]
	s_cbranch_vccz .LBB0_199
	s_barrier
